# P2 NOMAX loop: both K/V LDS-DMA issue blocks hoisted to the top of each half-iteration (prefetch lead 1.5 -> 2 halves), on top of P1 LDS tables + P2 pointer SALU
# speedup vs baseline: 1.0025x; 1.0025x over previous
; __device__ __forceinline__ void glds16(const void*gsrc,unsigned lds_dst){unsigned keep;
;   asm volatile("s_mov_b32 %0, m0\n\ts_mov_b32 m0, %2\n\ts_nop 0\n\tglobal_load_lds_dwordx4 %1, off\n\ts_mov_b32 m0, %0":"=&s"(keep):"v"(gsrc),"s"(lds_dst):"memory");}
.LBB0_1097:
	s_mov_b32 s7, s89
	s_add_u32 s98, s100, s24
	s_mov_b32 s88, s38
	s_addc_u32 s99, s101, s25
	s_mov_b32 s37, s87
	v_add_u32_e32 v198, s36, v233
	ds_read_b64_tr_b16 v[200:201], v198 offset:24576
	ds_read_b64_tr_b16 v[202:203], v198 offset:25088
	s_add_i32 s0, s87, s84
	s_mov_b32 s1, m0
	s_mov_b32 m0, s0
	s_nop 0
	global_load_lds_dwordx4 v196, s[98:99]
	s_mov_b32 m0, s1
	s_add_i32 s0, s89, s8
	s_mov_b32 s1, m0
	s_mov_b32 m0, s0
	s_nop 0
	global_load_lds_dwordx4 v194, s[98:99]
	s_mov_b32 m0, s1
	v_add_f32_e32 v98, v82, v83
	v_add_f32_e32 v98, v84, v98
	v_add_f32_e32 v98, v85, v98
	v_add_f32_e32 v98, v86, v98
	v_add_f32_e32 v98, v87, v98
	v_cvt_pk_bf16_f32 v158, v82, v83
	v_cvt_pk_bf16_f32 v159, v84, v85
	s_waitcnt lgkmcnt(9)
	v_mfma_f32_32x32x16_bf16 v[114:129], v[190:193], v[130:133], v[50:65]
	ds_read_b64_tr_b16 v[82:83], v198 offset:28672
	ds_read_b64_tr_b16 v[84:85], v198 offset:29184
	v_add_f32_e32 v98, v88, v98
	v_add_f32_e32 v98, v89, v98
	v_add_f32_e32 v98, v90, v98
	v_add_f32_e32 v146, v91, v98
	s_waitcnt lgkmcnt(10)
	v_mfma_f32_32x32x16_bf16 v[98:113], v[186:189], v[130:133], v[50:65]
	v_cvt_pk_bf16_f32 v160, v86, v87
	v_cvt_pk_bf16_f32 v161, v88, v89
	ds_read_b64_tr_b16 v[86:87], v198 offset:25600
	ds_read_b64_tr_b16 v[88:89], v198 offset:26112
	v_add_f32_e32 v146, v92, v146
	v_add_f32_e32 v146, v93, v146
	v_add_f32_e32 v146, v94, v146
	v_add_f32_e32 v146, v95, v146
	v_cvt_pk_bf16_f32 v154, v90, v91
	v_cvt_pk_bf16_f32 v155, v92, v93
	s_waitcnt lgkmcnt(11)
	v_mfma_f32_32x32x16_bf16 v[114:129], v[182:185], v[134:137], v[114:129]
	ds_read_b64_tr_b16 v[90:91], v198 offset:29696
	ds_read_b64_tr_b16 v[92:93], v198 offset:30208
	s_waitcnt lgkmcnt(12)
	v_mfma_f32_32x32x16_bf16 v[98:113], v[178:181], v[134:137], v[98:113]
	v_add_f32_e32 v146, v96, v146
	v_add_f32_e32 v146, v97, v146
	v_add_f32_e32 v146, v66, v146
	v_add_f32_e32 v146, v67, v146
	v_cvt_pk_bf16_f32 v156, v94, v95
	v_cvt_pk_bf16_f32 v157, v96, v97
	ds_read_b64_tr_b16 v[94:95], v198 offset:26624
	ds_read_b64_tr_b16 v[96:97], v198 offset:27136
	v_add_f32_e32 v146, v68, v146
	v_add_f32_e32 v146, v69, v146
	v_add_f32_e32 v146, v70, v146
	v_add_f32_e32 v146, v71, v146
	v_cvt_pk_bf16_f32 v150, v66, v67
	v_cvt_pk_bf16_f32 v151, v68, v69
	s_waitcnt lgkmcnt(13)
	v_mfma_f32_32x32x16_bf16 v[114:129], v[174:177], v[138:141], v[114:129]
	ds_read_b64_tr_b16 v[66:67], v198 offset:30720
	ds_read_b64_tr_b16 v[68:69], v198 offset:31232
	s_waitcnt lgkmcnt(14)
	v_mfma_f32_32x32x16_bf16 v[98:113], v[170:173], v[138:141], v[98:113]
	v_add_f32_e32 v146, v72, v146
	v_add_f32_e32 v146, v73, v146
	v_add_f32_e32 v146, v74, v146
	v_add_f32_e32 v146, v75, v146
	v_cvt_pk_bf16_f32 v152, v70, v71
	v_cvt_pk_bf16_f32 v153, v72, v73
	ds_read_b64_tr_b16 v[70:71], v198 offset:27648
	ds_read_b64_tr_b16 v[72:73], v198 offset:28160
	v_add_f32_e32 v146, v76, v146
	v_add_f32_e32 v146, v77, v146
	v_add_f32_e32 v146, v78, v146
	v_add_f32_e32 v170, v79, v146
	v_cvt_pk_bf16_f32 v146, v74, v75
	v_cvt_pk_bf16_f32 v147, v76, v77
	s_waitcnt lgkmcnt(14)
	v_mfma_f32_32x32x16_bf16 v[114:129], v[166:169], v[142:145], v[114:129]
	ds_read_b64_tr_b16 v[74:75], v198 offset:31744
	ds_read_b64_tr_b16 v[76:77], v198 offset:32256
	v_mfma_f32_32x32x16_bf16 v[98:113], v[162:165], v[142:145], v[98:113]
	v_add_f32_e32 v148, v80, v170
	v_add_f32_e32 v148, v81, v148
	v_add_f32_e32 v198, 0, v148
	v_cvt_pk_bf16_f32 v148, v78, v79
	v_cvt_pk_bf16_f32 v149, v80, v81
	s_waitcnt lgkmcnt(14)
	v_mfma_f32_32x32x16_bf16 v[18:33], v[158:161], v[200:203], v[18:33]
	v_exp_f32_e32 v114, v114
	v_exp_f32_e32 v115, v115
	v_exp_f32_e32 v116, v116
	v_exp_f32_e32 v117, v117
	s_waitcnt lgkmcnt(12)
	v_mfma_f32_32x32x16_bf16 v[34:49], v[158:161], v[82:85], v[34:49]
	v_exp_f32_e32 v118, v118
	v_exp_f32_e32 v119, v119
	v_exp_f32_e32 v120, v120
	v_exp_f32_e32 v121, v121
	v_add_u32_e32 v82, s7, v232
	ds_read_b128 v[78:81], v82
	ds_read_b128 v[162:165], v82 offset:512
	s_waitcnt lgkmcnt(12)
	v_mfma_f32_32x32x16_bf16 v[18:33], v[154:157], v[86:89], v[18:33]
	v_exp_f32_e32 v122, v122
	v_exp_f32_e32 v123, v123
	v_exp_f32_e32 v124, v124
	v_exp_f32_e32 v125, v125
	ds_read_b128 v[166:169], v82 offset:2048
	ds_read_b128 v[170:173], v82 offset:2560
	s_waitcnt lgkmcnt(12)
	v_mfma_f32_32x32x16_bf16 v[34:49], v[154:157], v[90:93], v[34:49]
	v_exp_f32_e32 v126, v126
	v_exp_f32_e32 v127, v127
	v_exp_f32_e32 v128, v128
	v_exp_f32_e32 v129, v129
	ds_read_b128 v[174:177], v82 offset:4096
	ds_read_b128 v[178:181], v82 offset:4608
	s_waitcnt lgkmcnt(12)
	v_mfma_f32_32x32x16_bf16 v[18:33], v[150:153], v[94:97], v[18:33]
	v_exp_f32_e32 v98, v98
	v_exp_f32_e32 v99, v99
	v_exp_f32_e32 v100, v100
	v_exp_f32_e32 v101, v101
	ds_read_b128 v[182:185], v82 offset:6144
	ds_read_b128 v[186:189], v82 offset:6656
	s_waitcnt lgkmcnt(12)
	v_mfma_f32_32x32x16_bf16 v[34:49], v[150:153], v[66:69], v[34:49]
	v_exp_f32_e32 v102, v102
	v_exp_f32_e32 v103, v103
	v_exp_f32_e32 v104, v104
	v_exp_f32_e32 v105, v105
	s_waitcnt lgkmcnt(10)
	v_mfma_f32_32x32x16_bf16 v[18:33], v[146:149], v[70:73], v[18:33]
	v_exp_f32_e32 v106, v106
	v_exp_f32_e32 v107, v107
	v_exp_f32_e32 v108, v108
	v_exp_f32_e32 v109, v109
	s_waitcnt lgkmcnt(8)
	v_mfma_f32_32x32x16_bf16 v[34:49], v[146:149], v[74:77], v[34:49]
	v_exp_f32_e32 v110, v110
	v_exp_f32_e32 v111, v111
	v_exp_f32_e32 v112, v112
	v_exp_f32_e32 v113, v113
	s_waitcnt vmcnt(2) lgkmcnt(0)
	s_barrier
; #define WAIT_BAR(N) asm volatile("s_waitcnt vmcnt(" #N ") lgkmcnt(0)\n\ts_barrier":::"memory")
;   #define RESC() do{ if(resc){ asm volatile("s_waitcnt lgkmcnt(0)":::"memory"); \
;       _Pragma("unroll") for(int d_=0;d_<2;++d_) _Pragma("unroll") for(int r=0;r<16;++r)o[d_][r]*=wsf[crow(r,hi)]; } }while(0)
;   #define ROT() do{sl_prev=sl_cur;sl_cur=sl_next;sl_next=(sl_next==(NSLOT-1)*SLOTB)?0:sl_next+SLOTB;}while(0)
; template<int THRL,bool NOMAX> __device__ __forceinline__ void attn_unit(long rowbase,int NT,int h,int qb,const bf16*Q,const bf16*__restrict__ Kh,const bf16*__restrict__ Vh,bf16*O,char*shm,
;     bool first,bool has_next,long n_rowbase,int n_h,int n_qb,const bf16*__restrict__ n_Kh,bf16x8 (&qr)[4]){
;     ...
;   for(;t+5<NT;t+=2){
;     STEP(pB0,pB1,pA0,pA1,t,true,true,true);     WAIT_BAR(2); RESC(); ROT();
;     STEP(pA0,pA1,pB0,pB1,t+1,true,true,true);   WAIT_BAR(2); RESC(); ROT();
;   }
	s_add_i32 s0, s89, 0x2000
	s_cmpk_lg_i32 s89, 0x4000
	s_cselect_b32 s87, s0, 0
	v_add_u32_e32 v199, s37, v233
	ds_read_b64_tr_b16 v[190:191], v199 offset:24576
	ds_read_b64_tr_b16 v[192:193], v199 offset:25088
	s_add_i32 s0, s89, s84
	s_mov_b32 s1, m0
	s_mov_b32 m0, s0
	s_nop 0
	global_load_lds_dwordx4 v196, s[100:101]
	s_mov_b32 m0, s1
	s_add_i32 s0, s87, s8
	s_mov_b32 s1, m0
	s_mov_b32 m0, s0
	s_nop 0
	global_load_lds_dwordx4 v194, s[100:101]
	s_mov_b32 m0, s1
	s_waitcnt lgkmcnt(9)
	v_mfma_f32_32x32x16_bf16 v[82:97], v[78:81], v[130:133], v[50:65]
	v_add_f32_e32 v66, v114, v115
	v_add_f32_e32 v66, v116, v66
	v_add_f32_e32 v66, v117, v66
	v_add_f32_e32 v66, v118, v66
	v_add_f32_e32 v66, v119, v66
	v_cvt_pk_bf16_f32 v158, v114, v115
	v_cvt_pk_bf16_f32 v159, v116, v117
	ds_read_b64_tr_b16 v[114:115], v199 offset:28672
	ds_read_b64_tr_b16 v[116:117], v199 offset:29184
	v_add_f32_e32 v66, v120, v66
	v_add_f32_e32 v66, v121, v66
	v_add_f32_e32 v66, v122, v66
	v_add_f32_e32 v146, v123, v66
	s_waitcnt lgkmcnt(10)
	v_mfma_f32_32x32x16_bf16 v[66:81], v[162:165], v[130:133], v[50:65]
	v_cvt_pk_bf16_f32 v160, v118, v119
	v_cvt_pk_bf16_f32 v161, v120, v121
	ds_read_b64_tr_b16 v[118:119], v199 offset:25600
	ds_read_b64_tr_b16 v[120:121], v199 offset:26112
	s_waitcnt lgkmcnt(11)
	v_mfma_f32_32x32x16_bf16 v[82:97], v[166:169], v[134:137], v[82:97]
	v_add_f32_e32 v146, v124, v146
	v_add_f32_e32 v146, v125, v146
	v_add_f32_e32 v146, v126, v146
	v_add_f32_e32 v146, v127, v146
	v_cvt_pk_bf16_f32 v154, v122, v123
	v_cvt_pk_bf16_f32 v155, v124, v125
	ds_read_b64_tr_b16 v[122:123], v199 offset:29696
	ds_read_b64_tr_b16 v[124:125], v199 offset:30208
	s_waitcnt lgkmcnt(12)
	v_mfma_f32_32x32x16_bf16 v[66:81], v[170:173], v[134:137], v[66:81]
	v_add_f32_e32 v146, v128, v146
	v_add_f32_e32 v146, v129, v146
	v_add_f32_e32 v146, v98, v146
	v_add_f32_e32 v146, v99, v146
	v_cvt_pk_bf16_f32 v156, v126, v127
	v_cvt_pk_bf16_f32 v157, v128, v129
	ds_read_b64_tr_b16 v[126:127], v199 offset:26624
	ds_read_b64_tr_b16 v[128:129], v199 offset:27136
	s_waitcnt lgkmcnt(13)
	v_mfma_f32_32x32x16_bf16 v[82:97], v[174:177], v[138:141], v[82:97]
	v_add_f32_e32 v146, v100, v146
	v_add_f32_e32 v146, v101, v146
	v_add_f32_e32 v146, v102, v146
	v_add_f32_e32 v146, v103, v146
	v_cvt_pk_bf16_f32 v150, v98, v99
	v_cvt_pk_bf16_f32 v151, v100, v101
	ds_read_b64_tr_b16 v[98:99], v199 offset:30720
	ds_read_b64_tr_b16 v[100:101], v199 offset:31232
	s_waitcnt lgkmcnt(14)
	v_mfma_f32_32x32x16_bf16 v[66:81], v[178:181], v[138:141], v[66:81]
	v_add_f32_e32 v146, v104, v146
	v_add_f32_e32 v146, v105, v146
	v_add_f32_e32 v146, v106, v146
	v_add_f32_e32 v146, v107, v146
	v_cvt_pk_bf16_f32 v152, v102, v103
	v_cvt_pk_bf16_f32 v153, v104, v105
	ds_read_b64_tr_b16 v[102:103], v199 offset:27648
	ds_read_b64_tr_b16 v[104:105], v199 offset:28160
	s_waitcnt lgkmcnt(14)
	v_mfma_f32_32x32x16_bf16 v[82:97], v[182:185], v[142:145], v[82:97]
	v_add_f32_e32 v146, v108, v146
	v_add_f32_e32 v146, v109, v146
	v_add_f32_e32 v146, v110, v146
	v_add_f32_e32 v162, v111, v146
	v_cvt_pk_bf16_f32 v146, v106, v107
	v_cvt_pk_bf16_f32 v147, v108, v109
	ds_read_b64_tr_b16 v[106:107], v199 offset:31744
	ds_read_b64_tr_b16 v[108:109], v199 offset:32256
	v_mfma_f32_32x32x16_bf16 v[66:81], v[186:189], v[142:145], v[66:81]
	v_add_f32_e32 v148, v112, v162
	v_add_f32_e32 v148, v113, v148
	v_add_f32_e32 v199, 0, v148
	v_cvt_pk_bf16_f32 v148, v110, v111
	v_cvt_pk_bf16_f32 v149, v112, v113
	s_waitcnt lgkmcnt(14)
	v_mfma_f32_32x32x16_bf16 v[18:33], v[158:161], v[190:193], v[18:33]
	v_exp_f32_e32 v82, v82
	v_exp_f32_e32 v83, v83
	v_exp_f32_e32 v84, v84
	v_exp_f32_e32 v85, v85
	s_waitcnt lgkmcnt(12)
	v_mfma_f32_32x32x16_bf16 v[34:49], v[158:161], v[114:117], v[34:49]
	v_exp_f32_e32 v86, v86
	v_exp_f32_e32 v87, v87
	v_exp_f32_e32 v88, v88
	v_exp_f32_e32 v89, v89
	v_add_u32_e32 v110, s87, v232
	ds_read_b128 v[190:193], v110
	ds_read_b128 v[186:189], v110 offset:512
	s_waitcnt lgkmcnt(12)
	v_mfma_f32_32x32x16_bf16 v[18:33], v[154:157], v[118:121], v[18:33]
	v_exp_f32_e32 v90, v90
	v_exp_f32_e32 v91, v91
	v_exp_f32_e32 v92, v92
	v_exp_f32_e32 v93, v93
	ds_read_b128 v[182:185], v110 offset:2048
	ds_read_b128 v[178:181], v110 offset:2560
	s_waitcnt lgkmcnt(12)
	v_mfma_f32_32x32x16_bf16 v[34:49], v[154:157], v[122:125], v[34:49]
	v_exp_f32_e32 v94, v94
	v_exp_f32_e32 v95, v95
	v_exp_f32_e32 v96, v96
	v_exp_f32_e32 v97, v97
	ds_read_b128 v[174:177], v110 offset:4096
	ds_read_b128 v[170:173], v110 offset:4608
	s_waitcnt lgkmcnt(12)
	v_mfma_f32_32x32x16_bf16 v[18:33], v[150:153], v[126:129], v[18:33]
	v_exp_f32_e32 v66, v66
	v_exp_f32_e32 v67, v67
	v_exp_f32_e32 v68, v68
	v_exp_f32_e32 v69, v69
	ds_read_b128 v[166:169], v110 offset:6144
	ds_read_b128 v[162:165], v110 offset:6656
	s_waitcnt lgkmcnt(12)
	v_mfma_f32_32x32x16_bf16 v[34:49], v[150:153], v[98:101], v[34:49]
	v_exp_f32_e32 v70, v70
	v_exp_f32_e32 v71, v71
	v_exp_f32_e32 v72, v72
	v_exp_f32_e32 v73, v73
	s_waitcnt lgkmcnt(10)
	v_mfma_f32_32x32x16_bf16 v[18:33], v[146:149], v[102:105], v[18:33]
	v_exp_f32_e32 v74, v74
	v_exp_f32_e32 v75, v75
	v_exp_f32_e32 v76, v76
	v_exp_f32_e32 v77, v77
	s_waitcnt lgkmcnt(8)
	v_mfma_f32_32x32x16_bf16 v[34:49], v[146:149], v[106:109], v[34:49]
	v_exp_f32_e32 v78, v78
	v_exp_f32_e32 v79, v79
	v_exp_f32_e32 v80, v80
	v_exp_f32_e32 v81, v81
	s_add_i32 s0, s87, 0x2000
	s_waitcnt vmcnt(2) lgkmcnt(0)
	s_barrier
	s_cmpk_lg_i32 s87, 0x4000
	v_add_f32_e32 v102, v206, v198
	s_mov_b32 s36, s89
	s_cselect_b32 s89, s0, 0
	s_add_i32 s6, s6, 2
	s_add_i32 s38, s38, 2
	s_add_u32 s100, s100, s14
	s_addc_u32 s101, s101, s15
	s_cmp_ge_u32 s6, s82
	v_add_f32_e32 v206, v102, v199
	s_cbranch_scc0 .LBB0_1097
	s_sub_u32 s98, s100, s62
	s_subb_u32 s99, s101, s63
	s_sub_u32 s98, s98, s14
	s_subb_u32 s99, s99, s15
	v_lshl_add_u64 v[226:227], v[226:227], 0, s[98:99]
	v_lshl_add_u64 v[228:229], v[228:229], 0, s[98:99]
	s_add_i32 s0, s6, -4
	s_cmp_ge_u32 s0, s82
	s_cbranch_scc1 .LBB0_1132
	s_add_i32 s90, s6, -5
